# DA latent main loop: LDS DMA ring K/V sharing + 2-accumulator software pipelining (QK(t+1) MFMAs under row-max VALU, PV under exp/sum), lazy rescale in this loop, max3 tree
# speedup vs baseline: 1.0239x; 1.0117x over previous
.LBB0_711:
	v_sub_f32_e32 v0, v80, v208
	v_sub_f32_e32 v80, v82, v208
	v_sub_f32_e32 v15, v81, v208
	v_exp_f32_e32 v81, v80
	v_sub_f32_e32 v80, v83, v208
	v_exp_f32_e32 v82, v80
	v_sub_f32_e32 v80, v84, v208
	v_exp_f32_e32 v83, v80
	v_sub_f32_e32 v80, v85, v208
	v_exp_f32_e32 v84, v80
	v_sub_f32_e32 v80, v86, v208
	v_exp_f32_e32 v85, v80
	v_sub_f32_e32 v80, v87, v208
	v_exp_f32_e32 v14, v0
	v_exp_f32_e32 v86, v80
	v_sub_f32_e32 v80, v88, v208
	v_exp_f32_e32 v15, v15
	v_exp_f32_e32 v87, v80
	v_sub_f32_e32 v80, v89, v208
	v_exp_f32_e32 v88, v80
	v_sub_f32_e32 v80, v90, v208
	v_exp_f32_e32 v89, v80
	v_sub_f32_e32 v80, v91, v208
	v_add_f32_e32 v0, 0, v14
	v_exp_f32_e32 v90, v80
	v_sub_f32_e32 v80, v92, v208
	v_add_f32_e32 v0, v15, v0
	v_exp_f32_e32 v91, v80
	v_sub_f32_e32 v80, v93, v208
	v_add_f32_e32 v0, v81, v0
	v_exp_f32_e32 v92, v80
	v_sub_f32_e32 v80, v94, v208
	v_add_f32_e32 v0, v82, v0
	v_exp_f32_e32 v93, v80
	v_sub_f32_e32 v80, v95, v208
	v_add_f32_e32 v0, v83, v0
	v_exp_f32_e32 v94, v80
	v_cvt_pk_bf16_f32 v80, v14, v15
	v_cvt_pk_bf16_f32 v81, v81, v82
	v_cvt_pk_bf16_f32 v82, v83, v84
	v_cvt_pk_bf16_f32 v83, v85, v86
	v_add_f32_e32 v0, v84, v0
	v_add_f32_e32 v0, v85, v0
	s_waitcnt vmcnt(5)
	v_mfma_f32_32x32x16_bf16 v[48:63], v[120:123], v[80:83], v[48:63]
	v_add_f32_e32 v0, v86, v0
	v_add_f32_e32 v0, v87, v0
	v_cvt_pk_bf16_f32 v84, v87, v88
	v_cvt_pk_bf16_f32 v85, v89, v90
	v_cvt_pk_bf16_f32 v86, v91, v92
	v_cvt_pk_bf16_f32 v87, v93, v94
	v_add_f32_e32 v0, v88, v0
	s_waitcnt vmcnt(3)
	v_mfma_f32_32x32x16_bf16 v[32:47], v[2:5], v[80:83], v[32:47]
	v_lshl_add_u64 v[2:3], v[154:155], 0, s[24:25]
	v_add_f32_e32 v0, v89, v0
	v_add_f32_e32 v0, v90, v0
	v_add_f32_e32 v0, v91, v0
	v_add_f32_e32 v0, v92, v0
	v_add_f32_e32 v0, v93, v0
	v_add_f32_e32 v0, v94, v0
	v_mfma_f32_32x32x16_bf16 v[48:63], v[10:13], v[84:87], v[48:63]
	v_add_f32_e32 v0, v209, v0
	s_mov_b32 s13, 63
	s_mov_b64 s[24:25], s[18:19]
	s_mov_b64 s[26:27], s[6:7]
	s_waitcnt vmcnt(2)
	v_mfma_f32_32x32x16_bf16 v[32:47], v[6:9], v[84:87], v[32:47]
	global_load_dwordx4 v[112:115], v[2:3], off
	global_load_dwordx4 v[10:13], v[2:3], off offset:1024
	global_load_dwordx4 v[6:9], v[2:3], off offset:2048
	s_nop 0
	global_load_dwordx4 v[2:5], v[2:3], off offset:3072
	v_mfma_f32_32x32x16_bf16 v[64:79], v[132:135], v[80:83], v[64:79]
	s_waitcnt vmcnt(5)
	v_mfma_f32_32x32x16_bf16 v[16:31], v[116:119], v[80:83], v[16:31]
	v_mfma_f32_32x32x16_bf16 v[64:79], v[124:127], v[84:87], v[64:79]
	s_waitcnt vmcnt(4)
	v_mfma_f32_32x32x16_bf16 v[16:31], v[128:131], v[84:87], v[16:31]
	s_waitcnt vmcnt(0)
	v_mfma_f32_32x32x16_bf16 v[80:95], v[112:115], v[108:111], 0
	v_mfma_f32_32x32x16_bf16 v[80:95], v[10:13], v[104:107], v[80:95]
	v_mfma_f32_32x32x16_bf16 v[80:95], v[6:9], v[100:103], v[80:95]
	v_mfma_f32_32x32x16_bf16 v[80:95], v[2:5], v[96:99], v[80:95]
	v_lshl_add_u64 v[14:15], s[24:25], 0, v[150:151]
	s_lshr_b32 s25, s52, 6
	s_and_b32 s24, s25, 3
	s_lshl_b32 s24, s24, 11
	global_load_dwordx4 v[112:115], v[14:15], off offset:-2048
	global_load_dwordx4 v[10:13], v[14:15], off offset:-1024
	global_load_dwordx4 v[6:9], v[14:15], off
	global_load_dwordx4 v[2:5], v[14:15], off offset:1024
	s_cmp_lt_u32 s25, 4
	s_cbranch_scc0 .Lmy_pp_vsrc
	s_add_u32 s28, s24, 0xf800
	s_mov_b32 s29, 0
	v_lshl_add_u64 v[242:243], s[18:19], 0, v[150:151]
	v_mov_b32_e32 v244, 0x10000
	s_branch .Lmy_pp_srcdone
.Lmy_pp_vsrc:
	s_add_u32 s28, s24, 0xe510000
	s_mov_b32 s29, 0
	v_lshl_add_u64 v[242:243], s[26:27], 0, v[150:151]
	v_mov_b32_e32 v244, 0x2000
.Lmy_pp_srcdone:
	s_nop 0
	v_lshl_add_u64 v[242:243], s[28:29], 0, v[242:243]
	v_mov_b32_e32 v245, 0
	v_add_u32_e32 v246, 0x10000, v150
	s_lshr_b32 s28, s25, 2
	s_lshl_b32 s28, s28, 12
	s_lshl_b32 s24, s25, 11
	s_add_i32 s24, s24, 0x10000
	v_add_u32_e32 v247, s28, v246
	s_mov_b32 m0, s24
	s_nop 0
	global_load_lds_dwordx4 v[242:243], off
	global_load_lds_dwordx4 v[242:243], off offset:1024
	v_lshl_add_u64 v[242:243], v[244:245], 0, v[242:243]
	s_add_i32 m0, s24, 0x4000
	s_nop 0
	global_load_lds_dwordx4 v[242:243], off
	global_load_lds_dwordx4 v[242:243], off offset:1024
	v_lshl_add_u64 v[242:243], v[244:245], 0, v[242:243]
	s_add_i32 m0, s24, 0x8000
	s_nop 0
	global_load_lds_dwordx4 v[242:243], off
	global_load_lds_dwordx4 v[242:243], off offset:1024
	v_lshl_add_u64 v[242:243], v[244:245], 0, v[242:243]
	s_add_i32 s24, s24, 0xc000
	s_lshr_b32 s29, s25, 2
	s_mov_b32 s25, 0
	s_waitcnt vmcnt(4)
	s_barrier
.Lmy_pp_loop2:
	v_add_u32_e32 v248, s25, v246
	v_add_u32_e32 v249, s25, v247
	ds_read_b128 v[144:147], v248 offset:8192
	ds_read_b128 v[136:139], v248 offset:10240
	ds_read_b128 v[132:135], v248 offset:12288
	ds_read_b128 v[116:119], v248 offset:14336
	ds_read_b128 v[128:131], v248 offset:9216
	ds_read_b128 v[140:143], v248 offset:11264
	ds_read_b128 v[124:127], v248 offset:13312
	ds_read_b128 v[120:123], v248 offset:15360
	v_mfma_f32_32x32x16_bf16 v[218:233], v[112:115], v[108:111], 0
	v_max3_f32 v14, v80, v81, v82
	v_max3_f32 v15, v83, v84, v85
	v_max3_f32 v209, v86, v87, v88
	s_mov_b32 m0, s24
	s_sub_i32 s28, 5, s29
	s_cmp_gt_u32 s13, s28
	s_cselect_b32 s28, -1, 0
	v_mfma_f32_32x32x16_bf16 v[218:233], v[10:13], v[104:107], v[218:233]
	v_max3_f32 v212, v89, v90, v91
	v_max3_f32 v14, v14, v92, v93
	v_max3_f32 v15, v15, v94, v95
	global_load_lds_dwordx4 v[242:243], off
	global_load_lds_dwordx4 v[242:243], off offset:1024
	v_mfma_f32_32x32x16_bf16 v[218:233], v[6:9], v[100:103], v[218:233]
	v_and_b32_e32 v244, s28, v244
	v_max3_f32 v14, v14, v15, v209
	v_max_f32_e32 v14, v14, v212
	v_lshl_add_u64 v[242:243], v[244:245], 0, v[242:243]
	v_mov_b32_e32 v15, v14
	s_add_i32 s24, s24, 0x4000
	s_and_b32 s24, s24, 0xffff
	v_mfma_f32_32x32x16_bf16 v[218:233], v[2:5], v[96:99], v[218:233]
	v_permlane32_swap_b32_e32 v14, v15
	ds_read_b128 v[112:115], v249
	ds_read_b128 v[10:13], v249 offset:1024
	ds_read_b128 v[6:9], v249 offset:2048
	ds_read_b128 v[2:5], v249 offset:3072
	s_or_b32 s24, s24, 0x10000
	s_add_i32 s25, s25, 0x4000
	s_and_b32 s25, s25, 0xc000
	v_max_f32_e32 v14, v14, v15
	v_add_f32_e32 v15, 0x41000000, v208
	v_cmp_gt_f32_e32 vcc, v14, v15
	s_cbranch_vccz .Lmy_pp_nors_a
	v_max_f32_e32 v15, v208, v14
	v_sub_f32_e32 v14, v208, v15
	v_exp_f32_e32 v14, v14
	v_mov_b32_e32 v208, v15
	s_nop 0
	v_mul_f32_e32 v0, v0, v14
	v_pk_mul_f32 v[78:79], v[78:79], v[14:15] op_sel_hi:[1,0]
	v_pk_mul_f32 v[76:77], v[76:77], v[14:15] op_sel_hi:[1,0]
	v_pk_mul_f32 v[74:75], v[74:75], v[14:15] op_sel_hi:[1,0]
	v_pk_mul_f32 v[72:73], v[72:73], v[14:15] op_sel_hi:[1,0]
	v_pk_mul_f32 v[70:71], v[70:71], v[14:15] op_sel_hi:[1,0]
	v_pk_mul_f32 v[68:69], v[68:69], v[14:15] op_sel_hi:[1,0]
	v_pk_mul_f32 v[66:67], v[66:67], v[14:15] op_sel_hi:[1,0]
	v_pk_mul_f32 v[64:65], v[64:65], v[14:15] op_sel_hi:[1,0]
	v_pk_mul_f32 v[62:63], v[62:63], v[14:15] op_sel_hi:[1,0]
	v_pk_mul_f32 v[60:61], v[60:61], v[14:15] op_sel_hi:[1,0]
	v_pk_mul_f32 v[58:59], v[58:59], v[14:15] op_sel_hi:[1,0]
	v_pk_mul_f32 v[56:57], v[56:57], v[14:15] op_sel_hi:[1,0]
	v_pk_mul_f32 v[54:55], v[54:55], v[14:15] op_sel_hi:[1,0]
	v_pk_mul_f32 v[52:53], v[52:53], v[14:15] op_sel_hi:[1,0]
	v_pk_mul_f32 v[50:51], v[50:51], v[14:15] op_sel_hi:[1,0]
	v_pk_mul_f32 v[48:49], v[48:49], v[14:15] op_sel_hi:[1,0]
	v_pk_mul_f32 v[46:47], v[46:47], v[14:15] op_sel_hi:[1,0]
	v_pk_mul_f32 v[44:45], v[44:45], v[14:15] op_sel_hi:[1,0]
	v_pk_mul_f32 v[42:43], v[42:43], v[14:15] op_sel_hi:[1,0]
	v_pk_mul_f32 v[40:41], v[40:41], v[14:15] op_sel_hi:[1,0]
	v_pk_mul_f32 v[38:39], v[38:39], v[14:15] op_sel_hi:[1,0]
	v_pk_mul_f32 v[36:37], v[36:37], v[14:15] op_sel_hi:[1,0]
	v_pk_mul_f32 v[34:35], v[34:35], v[14:15] op_sel_hi:[1,0]
	v_pk_mul_f32 v[32:33], v[32:33], v[14:15] op_sel_hi:[1,0]
	v_pk_mul_f32 v[30:31], v[30:31], v[14:15] op_sel_hi:[1,0]
	v_pk_mul_f32 v[28:29], v[28:29], v[14:15] op_sel_hi:[1,0]
	v_pk_mul_f32 v[26:27], v[26:27], v[14:15] op_sel_hi:[1,0]
	v_pk_mul_f32 v[24:25], v[24:25], v[14:15] op_sel_hi:[1,0]
	v_pk_mul_f32 v[22:23], v[22:23], v[14:15] op_sel_hi:[1,0]
	v_pk_mul_f32 v[20:21], v[20:21], v[14:15] op_sel_hi:[1,0]
	v_pk_mul_f32 v[18:19], v[18:19], v[14:15] op_sel_hi:[1,0]
	v_pk_mul_f32 v[16:17], v[16:17], v[14:15] op_sel_hi:[1,0]
.Lmy_pp_nors_a:
	s_cmp_eq_u32 s29, 0
	s_cbranch_scc1 .Lmy_pp_nbm_a
	s_waitcnt vmcnt(4) lgkmcnt(0)
	s_barrier
.Lmy_pp_nbm_a:
	v_sub_f32_e32 v14, v80, v208
	v_exp_f32_e32 v14, v14
	v_sub_f32_e32 v80, v81, v208
	v_exp_f32_e32 v80, v80
	v_sub_f32_e32 v81, v82, v208
	v_exp_f32_e32 v81, v81
	v_sub_f32_e32 v82, v83, v208
	v_exp_f32_e32 v82, v82
	v_sub_f32_e32 v83, v84, v208
	v_sub_f32_e32 v84, v85, v208
	v_sub_f32_e32 v85, v86, v208
	v_sub_f32_e32 v86, v87, v208
	v_add_f32_e32 v15, 0, v14
	v_exp_f32_e32 v83, v83
	v_exp_f32_e32 v84, v84
	v_exp_f32_e32 v85, v85
	v_exp_f32_e32 v86, v86
	v_add_f32_e32 v15, v80, v15
	v_add_f32_e32 v15, v81, v15
	v_add_f32_e32 v15, v82, v15
	v_add_f32_e32 v15, v83, v15
	v_cvt_pk_bf16_f32 v80, v14, v80
	v_cvt_pk_bf16_f32 v81, v81, v82
	v_cvt_pk_bf16_f32 v82, v83, v84
	v_cvt_pk_bf16_f32 v83, v85, v86
	v_sub_f32_e32 v87, v88, v208
	v_sub_f32_e32 v88, v89, v208
	s_waitcnt lgkmcnt(4)
	v_mfma_f32_32x32x16_bf16 v[64:79], v[144:147], v[80:83], v[64:79]
	v_sub_f32_e32 v89, v90, v208
	v_sub_f32_e32 v90, v91, v208
	v_sub_f32_e32 v91, v92, v208
	v_exp_f32_e32 v87, v87
	v_exp_f32_e32 v88, v88
	v_mfma_f32_32x32x16_bf16 v[48:63], v[136:139], v[80:83], v[48:63]
	v_sub_f32_e32 v92, v93, v208
	v_sub_f32_e32 v93, v94, v208
	v_sub_f32_e32 v94, v95, v208
	v_exp_f32_e32 v89, v89
	v_exp_f32_e32 v90, v90
	v_mfma_f32_32x32x16_bf16 v[32:47], v[132:135], v[80:83], v[32:47]
	v_exp_f32_e32 v91, v91
	v_exp_f32_e32 v92, v92
	v_exp_f32_e32 v93, v93
	v_exp_f32_e32 v94, v94
	v_mfma_f32_32x32x16_bf16 v[16:31], v[116:119], v[80:83], v[16:31]
	v_add_f32_e32 v15, v84, v15
	v_add_f32_e32 v15, v85, v15
	v_add_f32_e32 v15, v86, v15
	v_add_f32_e32 v15, v87, v15
	v_cvt_pk_bf16_f32 v84, v87, v88
	v_cvt_pk_bf16_f32 v85, v89, v90
	v_cvt_pk_bf16_f32 v86, v91, v92
	v_cvt_pk_bf16_f32 v87, v93, v94
	v_add_f32_e32 v15, v88, v15
	v_add_f32_e32 v15, v89, v15
	v_mfma_f32_32x32x16_bf16 v[64:79], v[128:131], v[84:87], v[64:79]
	v_add_f32_e32 v15, v90, v15
	v_add_f32_e32 v15, v91, v15
	s_add_i32 s13, s13, -1
	v_mfma_f32_32x32x16_bf16 v[48:63], v[140:143], v[84:87], v[48:63]
	v_add_f32_e32 v15, v92, v15
	v_add_f32_e32 v15, v93, v15
	v_mfma_f32_32x32x16_bf16 v[32:47], v[124:127], v[84:87], v[32:47]
	v_add_f32_e32 v15, v94, v15
	v_add_f32_e32 v0, v0, v15
	v_mfma_f32_32x32x16_bf16 v[16:31], v[120:123], v[84:87], v[16:31]
	s_cmp_lg_u32 s29, 0
	s_cbranch_scc1 .Lmy_pp_nbe_a
	s_waitcnt vmcnt(4) lgkmcnt(0)
	s_barrier
.Lmy_pp_nbe_a:
	v_add_u32_e32 v248, s25, v246
	v_add_u32_e32 v249, s25, v247
	ds_read_b128 v[144:147], v248 offset:8192
	ds_read_b128 v[136:139], v248 offset:10240
	ds_read_b128 v[132:135], v248 offset:12288
	ds_read_b128 v[116:119], v248 offset:14336
	ds_read_b128 v[128:131], v248 offset:9216
	ds_read_b128 v[140:143], v248 offset:11264
	ds_read_b128 v[124:127], v248 offset:13312
	ds_read_b128 v[120:123], v248 offset:15360
	v_mfma_f32_32x32x16_bf16 v[80:95], v[112:115], v[108:111], 0
	v_max3_f32 v14, v218, v219, v220
	v_max3_f32 v15, v221, v222, v223
	v_max3_f32 v209, v224, v225, v226
	s_mov_b32 m0, s24
	s_sub_i32 s28, 5, s29
	s_cmp_gt_u32 s13, s28
	s_cselect_b32 s28, -1, 0
	v_mfma_f32_32x32x16_bf16 v[80:95], v[10:13], v[104:107], v[80:95]
	v_max3_f32 v212, v227, v228, v229
	v_max3_f32 v14, v14, v230, v231
	v_max3_f32 v15, v15, v232, v233
	global_load_lds_dwordx4 v[242:243], off
	global_load_lds_dwordx4 v[242:243], off offset:1024
	v_mfma_f32_32x32x16_bf16 v[80:95], v[6:9], v[100:103], v[80:95]
	v_and_b32_e32 v244, s28, v244
	v_max3_f32 v14, v14, v15, v209
	v_max_f32_e32 v14, v14, v212
	v_lshl_add_u64 v[242:243], v[244:245], 0, v[242:243]
	v_mov_b32_e32 v15, v14
	s_add_i32 s24, s24, 0x4000
	s_and_b32 s24, s24, 0xffff
	v_mfma_f32_32x32x16_bf16 v[80:95], v[2:5], v[96:99], v[80:95]
	v_permlane32_swap_b32_e32 v14, v15
	ds_read_b128 v[112:115], v249
	ds_read_b128 v[10:13], v249 offset:1024
	ds_read_b128 v[6:9], v249 offset:2048
	ds_read_b128 v[2:5], v249 offset:3072
	s_or_b32 s24, s24, 0x10000
	s_add_i32 s25, s25, 0x4000
	s_and_b32 s25, s25, 0xc000
	v_max_f32_e32 v14, v14, v15
	v_add_f32_e32 v15, 0x41000000, v208
	v_cmp_gt_f32_e32 vcc, v14, v15
	s_cbranch_vccz .Lmy_pp_nors_b
	v_max_f32_e32 v15, v208, v14
	v_sub_f32_e32 v14, v208, v15
	v_exp_f32_e32 v14, v14
	v_mov_b32_e32 v208, v15
	s_nop 0
	v_mul_f32_e32 v0, v0, v14
	v_pk_mul_f32 v[78:79], v[78:79], v[14:15] op_sel_hi:[1,0]
	v_pk_mul_f32 v[76:77], v[76:77], v[14:15] op_sel_hi:[1,0]
	v_pk_mul_f32 v[74:75], v[74:75], v[14:15] op_sel_hi:[1,0]
	v_pk_mul_f32 v[72:73], v[72:73], v[14:15] op_sel_hi:[1,0]
	v_pk_mul_f32 v[70:71], v[70:71], v[14:15] op_sel_hi:[1,0]
	v_pk_mul_f32 v[68:69], v[68:69], v[14:15] op_sel_hi:[1,0]
	v_pk_mul_f32 v[66:67], v[66:67], v[14:15] op_sel_hi:[1,0]
	v_pk_mul_f32 v[64:65], v[64:65], v[14:15] op_sel_hi:[1,0]
	v_pk_mul_f32 v[62:63], v[62:63], v[14:15] op_sel_hi:[1,0]
	v_pk_mul_f32 v[60:61], v[60:61], v[14:15] op_sel_hi:[1,0]
	v_pk_mul_f32 v[58:59], v[58:59], v[14:15] op_sel_hi:[1,0]
	v_pk_mul_f32 v[56:57], v[56:57], v[14:15] op_sel_hi:[1,0]
	v_pk_mul_f32 v[54:55], v[54:55], v[14:15] op_sel_hi:[1,0]
	v_pk_mul_f32 v[52:53], v[52:53], v[14:15] op_sel_hi:[1,0]
	v_pk_mul_f32 v[50:51], v[50:51], v[14:15] op_sel_hi:[1,0]
	v_pk_mul_f32 v[48:49], v[48:49], v[14:15] op_sel_hi:[1,0]
	v_pk_mul_f32 v[46:47], v[46:47], v[14:15] op_sel_hi:[1,0]
	v_pk_mul_f32 v[44:45], v[44:45], v[14:15] op_sel_hi:[1,0]
	v_pk_mul_f32 v[42:43], v[42:43], v[14:15] op_sel_hi:[1,0]
	v_pk_mul_f32 v[40:41], v[40:41], v[14:15] op_sel_hi:[1,0]
	v_pk_mul_f32 v[38:39], v[38:39], v[14:15] op_sel_hi:[1,0]
	v_pk_mul_f32 v[36:37], v[36:37], v[14:15] op_sel_hi:[1,0]
	v_pk_mul_f32 v[34:35], v[34:35], v[14:15] op_sel_hi:[1,0]
	v_pk_mul_f32 v[32:33], v[32:33], v[14:15] op_sel_hi:[1,0]
	v_pk_mul_f32 v[30:31], v[30:31], v[14:15] op_sel_hi:[1,0]
	v_pk_mul_f32 v[28:29], v[28:29], v[14:15] op_sel_hi:[1,0]
	v_pk_mul_f32 v[26:27], v[26:27], v[14:15] op_sel_hi:[1,0]
	v_pk_mul_f32 v[24:25], v[24:25], v[14:15] op_sel_hi:[1,0]
	v_pk_mul_f32 v[22:23], v[22:23], v[14:15] op_sel_hi:[1,0]
	v_pk_mul_f32 v[20:21], v[20:21], v[14:15] op_sel_hi:[1,0]
	v_pk_mul_f32 v[18:19], v[18:19], v[14:15] op_sel_hi:[1,0]
	v_pk_mul_f32 v[16:17], v[16:17], v[14:15] op_sel_hi:[1,0]

.Lmy_pp_nbm_b:
	v_sub_f32_e32 v14, v218, v208
	v_exp_f32_e32 v14, v14
	v_sub_f32_e32 v218, v219, v208
	v_exp_f32_e32 v218, v218
	v_sub_f32_e32 v219, v220, v208
	v_exp_f32_e32 v219, v219
	v_sub_f32_e32 v220, v221, v208
	v_exp_f32_e32 v220, v220
	v_sub_f32_e32 v221, v222, v208
	v_sub_f32_e32 v222, v223, v208
	v_sub_f32_e32 v223, v224, v208
	v_sub_f32_e32 v224, v225, v208
	v_add_f32_e32 v15, 0, v14
	v_exp_f32_e32 v221, v221
	v_exp_f32_e32 v222, v222
	v_exp_f32_e32 v223, v223
	v_exp_f32_e32 v224, v224
	v_add_f32_e32 v15, v218, v15
	v_add_f32_e32 v15, v219, v15
	v_add_f32_e32 v15, v220, v15
	v_add_f32_e32 v15, v221, v15
	v_cvt_pk_bf16_f32 v218, v14, v218
	v_cvt_pk_bf16_f32 v219, v219, v220
	v_cvt_pk_bf16_f32 v220, v221, v222
	v_cvt_pk_bf16_f32 v221, v223, v224
	v_sub_f32_e32 v225, v226, v208
	v_sub_f32_e32 v226, v227, v208
	s_waitcnt lgkmcnt(4)
	v_mfma_f32_32x32x16_bf16 v[64:79], v[144:147], v[218:221], v[64:79]
	v_sub_f32_e32 v227, v228, v208
	v_sub_f32_e32 v228, v229, v208
	v_sub_f32_e32 v229, v230, v208
	v_exp_f32_e32 v225, v225
	v_exp_f32_e32 v226, v226
	v_mfma_f32_32x32x16_bf16 v[48:63], v[136:139], v[218:221], v[48:63]
	v_sub_f32_e32 v230, v231, v208
	v_sub_f32_e32 v231, v232, v208
	v_sub_f32_e32 v232, v233, v208
	v_exp_f32_e32 v227, v227
	v_exp_f32_e32 v228, v228
	v_mfma_f32_32x32x16_bf16 v[32:47], v[132:135], v[218:221], v[32:47]
	v_exp_f32_e32 v229, v229
	v_exp_f32_e32 v230, v230
	v_exp_f32_e32 v231, v231
	v_exp_f32_e32 v232, v232
	v_mfma_f32_32x32x16_bf16 v[16:31], v[116:119], v[218:221], v[16:31]
	v_add_f32_e32 v15, v222, v15
	v_add_f32_e32 v15, v223, v15
	v_add_f32_e32 v15, v224, v15
	v_add_f32_e32 v15, v225, v15
	v_cvt_pk_bf16_f32 v222, v225, v226
	v_cvt_pk_bf16_f32 v223, v227, v228
	v_cvt_pk_bf16_f32 v224, v229, v230
	v_cvt_pk_bf16_f32 v225, v231, v232
	v_add_f32_e32 v15, v226, v15
	v_add_f32_e32 v15, v227, v15
	v_mfma_f32_32x32x16_bf16 v[64:79], v[128:131], v[222:225], v[64:79]
	v_add_f32_e32 v15, v228, v15
	v_add_f32_e32 v15, v229, v15
	s_add_i32 s13, s13, -1
	v_mfma_f32_32x32x16_bf16 v[48:63], v[140:143], v[222:225], v[48:63]
	v_add_f32_e32 v15, v230, v15
	v_add_f32_e32 v15, v231, v15
	v_mfma_f32_32x32x16_bf16 v[32:47], v[124:127], v[222:225], v[32:47]
	v_add_f32_e32 v15, v232, v15
	v_add_f32_e32 v0, v0, v15
	v_mfma_f32_32x32x16_bf16 v[16:31], v[120:123], v[222:225], v[16:31]
	s_cmp_lg_u32 s29, 0
	s_cbranch_scc1 .Lmy_pp_nbe_b
	s_waitcnt vmcnt(4) lgkmcnt(0)
	s_barrier
.Lmy_pp_nbe_b:
	s_cmp_gt_u32 s13, 1
	s_cbranch_scc1 .Lmy_pp_loop2
	v_add_u32_e32 v248, s25, v246
	v_add_u32_e32 v249, s25, v247
	ds_read_b128 v[144:147], v248 offset:8192
	ds_read_b128 v[136:139], v248 offset:10240
	ds_read_b128 v[132:135], v248 offset:12288
	ds_read_b128 v[116:119], v248 offset:14336
	ds_read_b128 v[128:131], v248 offset:9216
	ds_read_b128 v[140:143], v248 offset:11264
	ds_read_b128 v[124:127], v248 offset:13312
	ds_read_b128 v[120:123], v248 offset:15360
	v_mfma_f32_32x32x16_bf16 v[218:233], v[112:115], v[108:111], 0
	v_max3_f32 v14, v80, v81, v82
	v_max3_f32 v15, v83, v84, v85
	v_max3_f32 v209, v86, v87, v88
	s_mov_b32 m0, s24
	s_sub_i32 s28, 5, s29
	s_cmp_gt_u32 s13, s28
	s_cselect_b32 s28, -1, 0
	v_mfma_f32_32x32x16_bf16 v[218:233], v[10:13], v[104:107], v[218:233]
	v_max3_f32 v212, v89, v90, v91
	v_max3_f32 v14, v14, v92, v93
	v_max3_f32 v15, v15, v94, v95
	global_load_lds_dwordx4 v[242:243], off
	global_load_lds_dwordx4 v[242:243], off offset:1024
	v_mfma_f32_32x32x16_bf16 v[218:233], v[6:9], v[100:103], v[218:233]
	v_and_b32_e32 v244, s28, v244
	v_max3_f32 v14, v14, v15, v209
	v_max_f32_e32 v14, v14, v212
	v_lshl_add_u64 v[242:243], v[244:245], 0, v[242:243]
	v_mov_b32_e32 v15, v14
	s_add_i32 s24, s24, 0x4000
	s_and_b32 s24, s24, 0xffff
	v_mfma_f32_32x32x16_bf16 v[218:233], v[2:5], v[96:99], v[218:233]
	v_permlane32_swap_b32_e32 v14, v15
	s_or_b32 s24, s24, 0x10000
	s_add_i32 s25, s25, 0x4000
	s_and_b32 s25, s25, 0xc000
	v_max_f32_e32 v14, v14, v15
	v_add_f32_e32 v15, 0x41000000, v208
	v_cmp_gt_f32_e32 vcc, v14, v15
	s_cbranch_vccz .Lmy_pp_nors_t
	v_max_f32_e32 v15, v208, v14
	v_sub_f32_e32 v14, v208, v15
	v_exp_f32_e32 v14, v14
	v_mov_b32_e32 v208, v15
	s_nop 0
	v_mul_f32_e32 v0, v0, v14
	v_pk_mul_f32 v[78:79], v[78:79], v[14:15] op_sel_hi:[1,0]
	v_pk_mul_f32 v[76:77], v[76:77], v[14:15] op_sel_hi:[1,0]
	v_pk_mul_f32 v[74:75], v[74:75], v[14:15] op_sel_hi:[1,0]
	v_pk_mul_f32 v[72:73], v[72:73], v[14:15] op_sel_hi:[1,0]
	v_pk_mul_f32 v[70:71], v[70:71], v[14:15] op_sel_hi:[1,0]
	v_pk_mul_f32 v[68:69], v[68:69], v[14:15] op_sel_hi:[1,0]
	v_pk_mul_f32 v[66:67], v[66:67], v[14:15] op_sel_hi:[1,0]
	v_pk_mul_f32 v[64:65], v[64:65], v[14:15] op_sel_hi:[1,0]
	v_pk_mul_f32 v[62:63], v[62:63], v[14:15] op_sel_hi:[1,0]
	v_pk_mul_f32 v[60:61], v[60:61], v[14:15] op_sel_hi:[1,0]
	v_pk_mul_f32 v[58:59], v[58:59], v[14:15] op_sel_hi:[1,0]
	v_pk_mul_f32 v[56:57], v[56:57], v[14:15] op_sel_hi:[1,0]
	v_pk_mul_f32 v[54:55], v[54:55], v[14:15] op_sel_hi:[1,0]
	v_pk_mul_f32 v[52:53], v[52:53], v[14:15] op_sel_hi:[1,0]
	v_pk_mul_f32 v[50:51], v[50:51], v[14:15] op_sel_hi:[1,0]
	v_pk_mul_f32 v[48:49], v[48:49], v[14:15] op_sel_hi:[1,0]
	v_pk_mul_f32 v[46:47], v[46:47], v[14:15] op_sel_hi:[1,0]
	v_pk_mul_f32 v[44:45], v[44:45], v[14:15] op_sel_hi:[1,0]
	v_pk_mul_f32 v[42:43], v[42:43], v[14:15] op_sel_hi:[1,0]
	v_pk_mul_f32 v[40:41], v[40:41], v[14:15] op_sel_hi:[1,0]
	v_pk_mul_f32 v[38:39], v[38:39], v[14:15] op_sel_hi:[1,0]
	v_pk_mul_f32 v[36:37], v[36:37], v[14:15] op_sel_hi:[1,0]
	v_pk_mul_f32 v[34:35], v[34:35], v[14:15] op_sel_hi:[1,0]
	v_pk_mul_f32 v[32:33], v[32:33], v[14:15] op_sel_hi:[1,0]
	v_pk_mul_f32 v[30:31], v[30:31], v[14:15] op_sel_hi:[1,0]
	v_pk_mul_f32 v[28:29], v[28:29], v[14:15] op_sel_hi:[1,0]
	v_pk_mul_f32 v[26:27], v[26:27], v[14:15] op_sel_hi:[1,0]
	v_pk_mul_f32 v[24:25], v[24:25], v[14:15] op_sel_hi:[1,0]
	v_pk_mul_f32 v[22:23], v[22:23], v[14:15] op_sel_hi:[1,0]
	v_pk_mul_f32 v[20:21], v[20:21], v[14:15] op_sel_hi:[1,0]
	v_pk_mul_f32 v[18:19], v[18:19], v[14:15] op_sel_hi:[1,0]
	v_pk_mul_f32 v[16:17], v[16:17], v[14:15] op_sel_hi:[1,0]

.Lmy_pp_nbm_t:
	v_sub_f32_e32 v14, v80, v208
	v_exp_f32_e32 v14, v14
	v_sub_f32_e32 v80, v81, v208
	v_exp_f32_e32 v80, v80
	v_sub_f32_e32 v81, v82, v208
	v_exp_f32_e32 v81, v81
	v_sub_f32_e32 v82, v83, v208
	v_exp_f32_e32 v82, v82
	v_sub_f32_e32 v83, v84, v208
	v_sub_f32_e32 v84, v85, v208
	v_sub_f32_e32 v85, v86, v208
	v_sub_f32_e32 v86, v87, v208
	v_add_f32_e32 v15, 0, v14
	v_exp_f32_e32 v83, v83
	v_exp_f32_e32 v84, v84
	v_exp_f32_e32 v85, v85
	v_exp_f32_e32 v86, v86
	v_add_f32_e32 v15, v80, v15
	v_add_f32_e32 v15, v81, v15
	v_add_f32_e32 v15, v82, v15
	v_add_f32_e32 v15, v83, v15
	v_cvt_pk_bf16_f32 v80, v14, v80
	v_cvt_pk_bf16_f32 v81, v81, v82
	v_cvt_pk_bf16_f32 v82, v83, v84
	v_cvt_pk_bf16_f32 v83, v85, v86
	v_sub_f32_e32 v87, v88, v208
	v_sub_f32_e32 v88, v89, v208
	s_waitcnt lgkmcnt(0)
	v_mfma_f32_32x32x16_bf16 v[64:79], v[144:147], v[80:83], v[64:79]
	v_sub_f32_e32 v89, v90, v208
	v_sub_f32_e32 v90, v91, v208
	v_sub_f32_e32 v91, v92, v208
	v_exp_f32_e32 v87, v87
	v_exp_f32_e32 v88, v88
	v_mfma_f32_32x32x16_bf16 v[48:63], v[136:139], v[80:83], v[48:63]
	v_sub_f32_e32 v92, v93, v208
	v_sub_f32_e32 v93, v94, v208
	v_sub_f32_e32 v94, v95, v208
	v_exp_f32_e32 v89, v89
	v_exp_f32_e32 v90, v90
	v_mfma_f32_32x32x16_bf16 v[32:47], v[132:135], v[80:83], v[32:47]
	v_exp_f32_e32 v91, v91
	v_exp_f32_e32 v92, v92
	v_exp_f32_e32 v93, v93
	v_exp_f32_e32 v94, v94
	v_mfma_f32_32x32x16_bf16 v[16:31], v[116:119], v[80:83], v[16:31]
	v_add_f32_e32 v15, v84, v15
	v_add_f32_e32 v15, v85, v15
	v_add_f32_e32 v15, v86, v15
	v_add_f32_e32 v15, v87, v15
	v_cvt_pk_bf16_f32 v84, v87, v88
	v_cvt_pk_bf16_f32 v85, v89, v90
	v_cvt_pk_bf16_f32 v86, v91, v92
	v_cvt_pk_bf16_f32 v87, v93, v94
	v_add_f32_e32 v15, v88, v15
	v_add_f32_e32 v15, v89, v15
	v_mfma_f32_32x32x16_bf16 v[64:79], v[128:131], v[84:87], v[64:79]
	v_add_f32_e32 v15, v90, v15
	v_add_f32_e32 v15, v91, v15
	s_add_i32 s13, s13, -1
	v_mfma_f32_32x32x16_bf16 v[48:63], v[140:143], v[84:87], v[48:63]
	v_add_f32_e32 v15, v92, v15
	v_add_f32_e32 v15, v93, v15
	v_mfma_f32_32x32x16_bf16 v[32:47], v[124:127], v[84:87], v[32:47]
	v_add_f32_e32 v15, v94, v15
	v_add_f32_e32 v0, v0, v15
	v_mfma_f32_32x32x16_bf16 v[16:31], v[120:123], v[84:87], v[16:31]
	s_cmp_lg_u32 s29, 0
	s_cbranch_scc1 .Lmy_pp_nbe_t
	s_waitcnt vmcnt(4) lgkmcnt(0)
	s_barrier
.Lmy_pp_nbe_t:
.LBB0_715:
	s_waitcnt vmcnt(3)
	v_mfma_f32_32x32x16_bf16 v[80:95], v[112:115], v[108:111], 0
	s_waitcnt vmcnt(2)
	v_mfma_f32_32x32x16_bf16 v[80:95], v[10:13], v[104:107], v[80:95]
	global_load_dwordx4 v[124:127], v[172:173], off
	global_load_dwordx4 v[120:123], v[174:175], off
	global_load_dwordx4 v[116:119], v[176:177], off
	global_load_dwordx4 v[112:115], v[178:179], off
	global_load_dwordx4 v[108:111], v[180:181], off
	global_load_dwordx4 v[104:107], v[182:183], off
	s_waitcnt vmcnt(7)
	v_mfma_f32_32x32x16_bf16 v[80:95], v[6:9], v[100:103], v[80:95]
	global_load_dwordx4 v[10:13], v[184:185], off
	global_load_dwordx4 v[6:9], v[186:187], off
	s_waitcnt vmcnt(8)
	v_mfma_f32_32x32x16_bf16 v[80:95], v[2:5], v[96:99], v[80:95]
	s_nop 11
	v_max_f32_e32 v2, v81, v81
	v_max_f32_e32 v3, v80, v80
	v_max_f32_e32 v2, v3, v2
	v_max_f32_e32 v3, v83, v83
	v_max_f32_e32 v4, v82, v82
	v_max_f32_e32 v3, v4, v3
	v_max_f32_e32 v4, v87, v87
	v_max_f32_e32 v5, v86, v86
	v_max_f32_e32 v4, v5, v4
	v_max3_f32 v4, v84, v85, v4
	v_max3_f32 v2, v2, v3, v4
	v_max_f32_e32 v3, v91, v91
	v_max_f32_e32 v4, v90, v90
	v_max_f32_e32 v3, v4, v3
	v_max_f32_e32 v4, v95, v95
	v_max_f32_e32 v5, v94, v94
	v_max_f32_e32 v4, v5, v4
	v_max3_f32 v3, v88, v89, v3
	v_max3_f32 v4, v92, v93, v4
	v_max3_f32 v2, v2, v3, v4
	v_mov_b32_e32 v3, v2
	s_nop 1
	v_permlane32_swap_b32_e32 v2, v3
	s_waitcnt lgkmcnt(0)
	v_max_f32_e32 v3, v3, v3
	v_max_f32_e32 v2, v2, v3
	v_cmp_gt_f32_e32 vcc, v2, v208
	s_cbranch_vccz .LBB0_717
	v_max_f32_e32 v2, v2, v2
	v_max_f32_e32 v3, v208, v208
	v_max_f32_e32 v3, v3, v2
	v_sub_f32_e32 v2, v208, v3
	v_exp_f32_e32 v2, v2
	v_mov_b32_e32 v208, v3
	v_mul_f32_e32 v0, v0, v2
	v_pk_mul_f32 v[78:79], v[78:79], v[2:3] op_sel_hi:[1,0]
	v_pk_mul_f32 v[76:77], v[76:77], v[2:3] op_sel_hi:[1,0]
	v_pk_mul_f32 v[74:75], v[74:75], v[2:3] op_sel_hi:[1,0]
	v_pk_mul_f32 v[72:73], v[72:73], v[2:3] op_sel_hi:[1,0]
	v_pk_mul_f32 v[70:71], v[70:71], v[2:3] op_sel_hi:[1,0]
	v_pk_mul_f32 v[68:69], v[68:69], v[2:3] op_sel_hi:[1,0]
	v_pk_mul_f32 v[66:67], v[66:67], v[2:3] op_sel_hi:[1,0]
	v_pk_mul_f32 v[64:65], v[64:65], v[2:3] op_sel_hi:[1,0]
	v_pk_mul_f32 v[62:63], v[62:63], v[2:3] op_sel_hi:[1,0]
	v_pk_mul_f32 v[60:61], v[60:61], v[2:3] op_sel_hi:[1,0]
	v_pk_mul_f32 v[58:59], v[58:59], v[2:3] op_sel_hi:[1,0]
	v_pk_mul_f32 v[56:57], v[56:57], v[2:3] op_sel_hi:[1,0]
	v_pk_mul_f32 v[54:55], v[54:55], v[2:3] op_sel_hi:[1,0]
	v_pk_mul_f32 v[52:53], v[52:53], v[2:3] op_sel_hi:[1,0]
	v_pk_mul_f32 v[50:51], v[50:51], v[2:3] op_sel_hi:[1,0]
	v_pk_mul_f32 v[48:49], v[48:49], v[2:3] op_sel_hi:[1,0]
	v_pk_mul_f32 v[46:47], v[46:47], v[2:3] op_sel_hi:[1,0]
	v_pk_mul_f32 v[44:45], v[44:45], v[2:3] op_sel_hi:[1,0]
	v_pk_mul_f32 v[42:43], v[42:43], v[2:3] op_sel_hi:[1,0]
	v_pk_mul_f32 v[40:41], v[40:41], v[2:3] op_sel_hi:[1,0]
	v_pk_mul_f32 v[38:39], v[38:39], v[2:3] op_sel_hi:[1,0]
	v_pk_mul_f32 v[36:37], v[36:37], v[2:3] op_sel_hi:[1,0]
	v_pk_mul_f32 v[34:35], v[34:35], v[2:3] op_sel_hi:[1,0]
	v_pk_mul_f32 v[32:33], v[32:33], v[2:3] op_sel_hi:[1,0]
	v_pk_mul_f32 v[30:31], v[30:31], v[2:3] op_sel_hi:[1,0]
	v_pk_mul_f32 v[28:29], v[28:29], v[2:3] op_sel_hi:[1,0]
	v_pk_mul_f32 v[26:27], v[26:27], v[2:3] op_sel_hi:[1,0]
	v_pk_mul_f32 v[24:25], v[24:25], v[2:3] op_sel_hi:[1,0]
	v_pk_mul_f32 v[22:23], v[22:23], v[2:3] op_sel_hi:[1,0]
	v_pk_mul_f32 v[20:21], v[20:21], v[2:3] op_sel_hi:[1,0]
	v_pk_mul_f32 v[18:19], v[18:19], v[2:3] op_sel_hi:[1,0]
	v_pk_mul_f32 v[16:17], v[16:17], v[2:3] op_sel_hi:[1,0]
